# attention item K staging: the four dependent load-wait-ds_write round trips become four masked loads in flight behind one wait (prologue de-serialisation in a new place), on top of v37
# baseline (speedup 1.0000x reference)
; #define LAS __attribute__((address_space(3)))
; #define OPAQUE_V(x) asm volatile("" : "+v"(x))
; __device__ __forceinline__ void attn_item(KP p, LAS unsigned char* lds, int l, int n, int hk) {
;     int tid_ = threadIdx.x; OPAQUE_V(tid_);
;     const int tid = tid_, wid = __builtin_amdgcn_readfirstlane(tid >> 6), lane = tid & 63, fr = lane & 15, fq = lane >> 4;
;     const bf16_t* HM = (const bf16_t*)(p->ws + WS_HM);
;     bf16_t* YC = (bf16_t*)(p->ws + WS_Y) + (size_t)2 * SEQ * 1024;
;     LAS bf16_t* Ks = (LAS bf16_t*)lds;
;     LAS unsigned* Vt32 = (LAS unsigned*)(lds + 36864);
;     LAS float* bias = (LAS float*)(lds + 36864 + 35840);
;     const int tokb = (n - 1) * 128;
;     for (int idx = tid; idx < 2048; idx += 512) { const int key = idx >> 3, pc = idx & 7; const int tok = tokb + key;
;         u32x4 v = (u32x4){0u, 0u, 0u, 0u}; if (tok >= 0) v = *(const u32x4*)(HM + (size_t)tok * HMW + C_K + hk * 64 + pc * 8);
;         *(LAS u32x4*)(Ks + key * 72 + pc * 8) = v; }
.LBB0_467:
	s_andn2_b64 vcc, exec, s[40:41]
	s_cbranch_vccnz .LBB0_516
	s_add_i32 s25, s92, 0xffffff40
	s_lshl_b32 s24, s25, 6
	v_mov_b32_e32 v10, v166
	s_and_b32 s61, s24, 0x7fffff80
	s_movk_i32 s6, 0x800
	s_and_b32 s63, s92, 1
	s_add_i32 s46, s61, 0xffffff80
	v_readfirstlane_b32 s62, v10
	v_cmp_gt_i32_e32 vcc, s6, v10
	s_and_saveexec_b64 s[40:41], vcc
	s_cbranch_execz .LBB0_473
	v_and_b32_e32 v2, 7, v10
	s_lshl_b32 s6, s63, 6
	v_lshlrev_b32_e32 v0, 3, v2
	v_lshl_add_u32 v6, v2, 4, 0
	s_mov_b64 s[42:43], 0
	s_lshl_b32 s6, s6, 1
	v_lshlrev_b32_e32 v0, 1, v0
	v_mov_b32_e32 v7, v10
	v_ashrrev_i32_e32 v8, 3, v10
	v_add_u32_e32 v9, s46, v8
	v_mov_b32_e32 v216, 0
	v_mov_b32_e32 v217, 0
	v_mov_b32_e32 v218, 0
	v_mov_b32_e32 v219, 0
	v_mov_b32_e32 v220, 0
	v_mov_b32_e32 v221, 0
	v_mov_b32_e32 v222, 0
	v_mov_b32_e32 v223, 0
	v_mov_b32_e32 v224, 0
	v_mov_b32_e32 v225, 0
	v_mov_b32_e32 v226, 0
	v_mov_b32_e32 v227, 0
	v_mov_b32_e32 v228, 0
	v_mov_b32_e32 v229, 0
	v_mov_b32_e32 v230, 0
	v_mov_b32_e32 v231, 0
	v_mov_b32_e32 v232, v9
	v_cmp_lt_i32_e32 vcc, -1, v232
	s_and_saveexec_b64 s[44:45], vcc
	v_mov_b64_e32 v[2:3], s[36:37]
	v_mad_u64_u32 v[2:3], s[64:65], v232, s50, v[2:3]
	v_lshl_add_u64 v[2:3], v[2:3], 0, s[6:7]
	v_lshl_add_u64 v[2:3], v[2:3], 0, v[0:1]
	v_add_co_u32_e32 v2, vcc, 0x2000, v2
	s_nop 1
	v_addc_co_u32_e32 v3, vcc, 0, v3, vcc
	global_load_dwordx4 v[216:219], v[2:3], off offset:2048
	s_mov_b64 exec, s[44:45]
	v_add_u32_e32 v232, 64, v9
	v_cmp_lt_i32_e32 vcc, -1, v232
	s_and_saveexec_b64 s[44:45], vcc
	v_mov_b64_e32 v[2:3], s[36:37]
	v_mad_u64_u32 v[2:3], s[64:65], v232, s50, v[2:3]
	v_lshl_add_u64 v[2:3], v[2:3], 0, s[6:7]
	v_lshl_add_u64 v[2:3], v[2:3], 0, v[0:1]
	v_add_co_u32_e32 v2, vcc, 0x2000, v2
	s_nop 1
	v_addc_co_u32_e32 v3, vcc, 0, v3, vcc
	global_load_dwordx4 v[220:223], v[2:3], off offset:2048
	s_mov_b64 exec, s[44:45]
	v_add_u32_e32 v232, 128, v9
	v_cmp_lt_i32_e32 vcc, -1, v232
	s_and_saveexec_b64 s[44:45], vcc
	v_mov_b64_e32 v[2:3], s[36:37]
	v_mad_u64_u32 v[2:3], s[64:65], v232, s50, v[2:3]
	v_lshl_add_u64 v[2:3], v[2:3], 0, s[6:7]
	v_lshl_add_u64 v[2:3], v[2:3], 0, v[0:1]
	v_add_co_u32_e32 v2, vcc, 0x2000, v2
	s_nop 1
	v_addc_co_u32_e32 v3, vcc, 0, v3, vcc
	global_load_dwordx4 v[224:227], v[2:3], off offset:2048
	s_mov_b64 exec, s[44:45]
	v_add_u32_e32 v232, 192, v9
	v_cmp_lt_i32_e32 vcc, -1, v232
	s_and_saveexec_b64 s[44:45], vcc
	v_mov_b64_e32 v[2:3], s[36:37]
	v_mad_u64_u32 v[2:3], s[64:65], v232, s50, v[2:3]
	v_lshl_add_u64 v[2:3], v[2:3], 0, s[6:7]
	v_lshl_add_u64 v[2:3], v[2:3], 0, v[0:1]
	v_add_co_u32_e32 v2, vcc, 0x2000, v2
	s_nop 1
	v_addc_co_u32_e32 v3, vcc, 0, v3, vcc
	global_load_dwordx4 v[228:231], v[2:3], off offset:2048
	s_mov_b64 exec, s[44:45]
	v_mul_u32_u24_e32 v8, 0x90, v8
	v_add_u32_e32 v8, v8, v6
	s_waitcnt vmcnt(0)
	ds_write_b128 v8, v[216:219]
	ds_write_b128 v8, v[220:223] offset:9216
	ds_write_b128 v8, v[224:227] offset:18432
	ds_write_b128 v8, v[228:231] offset:27648
